# l2norm butterfly: the two cross-row steps by v_permlane16/32_swap instead of LDS crossbar ops
# speedup vs baseline: 1.0015x; 1.0015x over previous
.LBB0_133:
	s_or_b64 exec, exec, s[28:29]
	s_add_i32 s47, s50, s5
	s_cmpk_gt_i32 s47, 0x7ff
	s_cselect_b64 s[44:45], -1, 0
	s_lshl_b32 s6, s47, 6
	s_and_b32 s6, s6, 0x7c0
	s_ashr_i32 s7, s47, 5
	s_or_b32 s6, s6, s7
	s_cmpk_lt_i32 s47, 0x800
	s_cselect_b32 s7, s6, s42
	s_and_b32 s10, s7, 63
	s_lshl_b32 s6, s7, 4
	s_lshl_b32 s8, s7, 2
	s_and_b32 s6, s6, 0xfffff000
	s_lshl_b32 s11, s10, 6
	s_and_b32 s8, s8, 0x300
	s_add_u32 s8, s88, s8
	s_addc_u32 s9, s89, 0
	s_cmp_lg_u32 s10, 0
	s_cselect_b64 s[28:29], -1, 0
	s_or_b32 s10, s11, s6
	s_add_i32 s10, s10, -3
	s_mul_i32 s11, s10, 0x1800
	s_mul_hi_i32 s34, s10, 0x1800
	s_add_u32 s8, s8, s11
	s_addc_u32 s9, s9, s34
	v_cmp_eq_u32_e64 s[56:57], v132, v139
	v_cmp_eq_u32_e64 s[58:59], v133, v140
	v_cmp_eq_u32_e64 s[60:61], v134, v141
	v_cmp_eq_u32_e64 s[62:63], v135, v142
	v_cmp_eq_u32_e64 s[64:65], v136, v143
	v_cmp_eq_u32_e64 s[66:67], v137, v144
	v_cmp_eq_u32_e64 s[68:69], v138, v145
	s_or_b64 s[56:57], s[56:57], s[28:29]
	s_or_b64 s[58:59], s[58:59], s[28:29]
	s_or_b64 s[60:61], s[60:61], s[28:29]
	s_or_b64 s[62:63], s[62:63], s[28:29]
	s_or_b64 s[64:65], s[64:65], s[28:29]
	s_or_b64 s[66:67], s[66:67], s[28:29]
	s_or_b64 s[68:69], s[68:69], s[28:29]
	v_cndmask_b32_e64 v2, v139, v132, s[56:57]
	v_cndmask_b32_e64 v3, v140, v133, s[58:59]
	v_cndmask_b32_e64 v4, v141, v134, s[60:61]
	v_cndmask_b32_e64 v5, v142, v135, s[62:63]
	v_cndmask_b32_e64 v6, v143, v136, s[64:65]
	v_cndmask_b32_e64 v7, v144, v137, s[66:67]
	v_cndmask_b32_e64 v8, v145, v138, s[68:69]
	global_load_dwordx4 v[38:41], v2, s[8:9]
	global_load_dwordx4 v[34:37], v3, s[8:9]
	global_load_dwordx4 v[46:49], v4, s[8:9]
	global_load_dwordx4 v[42:45], v5, s[8:9]
	global_load_dwordx4 v[54:57], v6, s[8:9]
	global_load_dwordx4 v[50:53], v7, s[8:9]
	global_load_dwordx4 v[58:61], v8, s[8:9]
	s_bfe_u32 s28, s7, 0x20006
	s_lshl_b32 s34, s28, 9
	v_lshl_add_u64 v[2:3], v[70:71], 0, s[34:35]
	v_add_co_u32_e32 v4, vcc, s90, v2
	s_movk_i32 s8, 0x3000
	s_nop 0
	v_addc_co_u32_e32 v5, vcc, 0, v3, vcc
	v_add_co_u32_e32 v6, vcc, s8, v2
	s_movk_i32 s8, 0x2000
	s_nop 0
	v_addc_co_u32_e32 v7, vcc, 0, v3, vcc
	v_add_co_u32_e32 v8, vcc, s97, v2
	s_lshl_b32 s7, s7, 6
	s_nop 0
	v_addc_co_u32_e32 v9, vcc, 0, v3, vcc
	v_add_co_u32_e32 v10, vcc, s8, v2
	s_movk_i32 s8, 0x5000
	s_nop 0
	v_addc_co_u32_e32 v11, vcc, 0, v3, vcc
	s_and_b32 s7, s7, 0xfc0
	v_add_co_u32_e32 v12, vcc, s8, v2
	s_lshl_b32 s34, s28, 2
	s_nop 0
	v_addc_co_u32_e32 v13, vcc, 0, v3, vcc
	global_load_dwordx2 v[74:75], v[10:11], off
	global_load_dwordx2 v[76:77], v[12:13], off
	global_load_dwordx2 v[64:65], v[10:11], off offset:2048
	global_load_dwordx2 v[78:79], v[6:7], off offset:2048
	global_load_dwordx2 v[86:87], v[2:3], off
	global_load_dwordx2 v[84:85], v[4:5], off offset:2048
	global_load_dwordx2 v[72:73], v[2:3], off offset:2048
	global_load_dwordx2 v[66:67], v[4:5], off
	global_load_dwordx2 v[80:81], v[8:9], off offset:-4096
	global_load_dwordx2 v[82:83], v[8:9], off offset:2048
	global_load_dwordx2 v[62:63], v[8:9], off
	global_load_dwordx2 v[68:69], v[12:13], off offset:2048
	v_or_b32_e32 v2, s7, v224
	v_or_b32_e32 v2, s6, v2
	v_ashrrev_i32_e32 v3, 31, v2
	v_readlane_b32 s6, v254, 22
	s_load_dwordx4 s[8:11], s[0:1], 0x60
	v_lshlrev_b64 v[2:3], 5, v[2:3]
	v_readlane_b32 s7, v254, 23
	s_nop 1
	v_lshl_add_u64 v[2:3], s[6:7], 0, v[2:3]
	s_or_b32 s6, s28, s18
	s_ashr_i32 s7, s6, 31
	s_lshl_b64 s[6:7], s[6:7], 2
	s_waitcnt lgkmcnt(0)
	s_add_u32 s10, s10, s6
	s_addc_u32 s11, s11, s7
	s_add_u32 s6, s8, s6
	v_lshl_add_u64 v[2:3], v[2:3], 0, s[34:35]
	s_addc_u32 s7, s9, s7
	s_lshl_b32 s34, s48, 10
	global_load_dword v99, v[2:3], off
	global_load_dword v98, v[2:3], off offset:16
	v_or_b32_e32 v2, s34, v93
	v_lshl_add_u32 v95, v2, 2, 0
	global_load_dword v100, v131, s[10:11]
	global_load_dword v97, v131, s[6:7]
	ds_read2st64_b32 v[30:31], v95 offset1:1
	ds_read2st64_b32 v[26:27], v95 offset0:128 offset1:129
	ds_read2st64_b32 v[28:29], v95 offset0:2 offset1:3
	ds_read2st64_b32 v[24:25], v95 offset0:4 offset1:5
	ds_read2st64_b32 v[22:23], v95 offset0:6 offset1:7
	ds_read2st64_b32 v[32:33], v95 offset0:130 offset1:131
	ds_read2st64_b32 v[20:21], v95 offset0:132 offset1:133
	ds_read2st64_b32 v[18:19], v95 offset0:134 offset1:135
	s_waitcnt lgkmcnt(6)
	v_pk_mul_f32 v[2:3], v[26:27], v[26:27]
	ds_read2st64_b32 v[14:15], v95 offset0:8 offset1:9
	ds_read2st64_b32 v[10:11], v95 offset0:136 offset1:137
	ds_read2st64_b32 v[12:13], v95 offset0:10 offset1:11
	ds_read2st64_b32 v[8:9], v95 offset0:12 offset1:13
	ds_read2st64_b32 v[6:7], v95 offset0:14 offset1:15
	v_add_f32_e32 v101, v2, v3
	s_waitcnt lgkmcnt(7)
	v_pk_mul_f32 v[2:3], v[32:33], v[32:33]
	v_mul_f32_e32 v96, v31, v31
	v_add_f32_e32 v105, v2, v3
	s_waitcnt lgkmcnt(6)
	v_pk_mul_f32 v[2:3], v[20:21], v[20:21]
	v_fmac_f32_e32 v96, v30, v30
	v_add_f32_e32 v107, v2, v3
	s_waitcnt lgkmcnt(5)
	v_pk_mul_f32 v[2:3], v[18:19], v[18:19]
	s_waitcnt lgkmcnt(3)
	v_pk_mul_f32 v[102:103], v[10:11], v[10:11]
	v_add_f32_e32 v109, v2, v3
	ds_read2st64_b32 v[16:17], v95 offset0:138 offset1:139
	ds_read2st64_b32 v[4:5], v95 offset0:140 offset1:141
	ds_read2st64_b32 v[2:3], v95 offset0:142 offset1:143
	v_add_f32_e32 v111, v102, v103
	s_waitcnt lgkmcnt(2)
	v_pk_mul_f32 v[102:103], v[16:17], v[16:17]
	v_mul_f32_e32 v104, v29, v29
	v_mul_f32_e32 v106, v25, v25
	v_mul_f32_e32 v108, v23, v23
	v_mul_f32_e32 v110, v15, v15
	v_mul_f32_e32 v112, v13, v13
	v_add_f32_e32 v113, v102, v103
	v_mul_f32_e32 v114, v9, v9
	s_waitcnt lgkmcnt(1)
	v_pk_mul_f32 v[102:103], v[4:5], v[4:5]
	v_mul_f32_e32 v116, v7, v7
	v_fmac_f32_e32 v104, v28, v28
	v_fmac_f32_e32 v106, v24, v24
	v_fmac_f32_e32 v108, v22, v22
	v_fmac_f32_e32 v110, v14, v14
	v_fmac_f32_e32 v112, v12, v12
	v_fmac_f32_e32 v114, v8, v8
	v_add_f32_e32 v115, v102, v103
	v_fmac_f32_e32 v116, v6, v6
	s_waitcnt lgkmcnt(0)
	v_pk_mul_f32 v[102:103], v[2:3], v[2:3]
	v_add_f32_e32 v102, v102, v103
	v_add_f32_dpp v96, v96, v96 row_ror:8 row_mask:0xf bank_mask:0xf
	v_add_f32_dpp v104, v104, v104 row_ror:8 row_mask:0xf bank_mask:0xf
	v_add_f32_dpp v106, v106, v106 row_ror:8 row_mask:0xf bank_mask:0xf
	v_add_f32_dpp v108, v108, v108 row_ror:8 row_mask:0xf bank_mask:0xf
	v_add_f32_dpp v110, v110, v110 row_ror:8 row_mask:0xf bank_mask:0xf
	v_add_f32_dpp v112, v112, v112 row_ror:8 row_mask:0xf bank_mask:0xf
	v_add_f32_dpp v114, v114, v114 row_ror:8 row_mask:0xf bank_mask:0xf
	v_add_f32_dpp v116, v116, v116 row_ror:8 row_mask:0xf bank_mask:0xf
	v_add_f32_dpp v96, v101, v101 row_ror:8 row_mask:0xf bank_mask:0xc
	v_add_f32_dpp v104, v105, v105 row_ror:8 row_mask:0xf bank_mask:0xc
	v_add_f32_dpp v106, v107, v107 row_ror:8 row_mask:0xf bank_mask:0xc
	v_add_f32_dpp v108, v109, v109 row_ror:8 row_mask:0xf bank_mask:0xc
	v_add_f32_dpp v110, v111, v111 row_ror:8 row_mask:0xf bank_mask:0xc
	v_add_f32_dpp v112, v113, v113 row_ror:8 row_mask:0xf bank_mask:0xc
	v_add_f32_dpp v114, v115, v115 row_ror:8 row_mask:0xf bank_mask:0xc
	v_add_f32_dpp v116, v102, v102 row_ror:8 row_mask:0xf bank_mask:0xc
	v_add_f32_dpp v96, v96, v96 row_ror:12 row_mask:0xf bank_mask:0xf
	v_add_f32_dpp v106, v106, v106 row_ror:12 row_mask:0xf bank_mask:0xf
	v_add_f32_dpp v110, v110, v110 row_ror:12 row_mask:0xf bank_mask:0xf
	v_add_f32_dpp v114, v114, v114 row_ror:12 row_mask:0xf bank_mask:0xf
	v_add_f32_dpp v96, v104, v104 row_ror:4 row_mask:0xf bank_mask:0xa
	v_add_f32_dpp v106, v108, v108 row_ror:4 row_mask:0xf bank_mask:0xa
	v_add_f32_dpp v110, v112, v112 row_ror:4 row_mask:0xf bank_mask:0xa
	v_add_f32_dpp v114, v116, v116 row_ror:4 row_mask:0xf bank_mask:0xa
	s_mov_b32 vcc_lo, 0xcccccccc
	s_mov_b32 vcc_hi, 0xcccccccc
	v_cndmask_b32_e32 v117, v96, v106, vcc
	v_cndmask_b32_e32 v118, v106, v96, vcc
	v_cndmask_b32_e32 v121, v110, v114, vcc
	v_cndmask_b32_e32 v122, v114, v110, vcc
	v_add_f32_dpp v96, v118, v117 quad_perm:[2,3,0,1] row_mask:0xf bank_mask:0xf
	s_nop 0
	v_add_f32_dpp v110, v122, v121 quad_perm:[2,3,0,1] row_mask:0xf bank_mask:0xf
	s_mov_b32 vcc_lo, 0xaaaaaaaa
	s_mov_b32 vcc_hi, 0xaaaaaaaa
	v_cndmask_b32_e32 v117, v96, v110, vcc
	v_cndmask_b32_e32 v118, v110, v96, vcc
	s_nop 1
	v_add_f32_dpp v120, v118, v117 quad_perm:[1,0,3,2] row_mask:0xf bank_mask:0xf
	v_mov_b32_e32 v117, v120
	s_mov_b32 vcc_lo, 0xff00ff00
	s_mov_b32 vcc_hi, 0xff00ff00
	s_nop 1
	v_permlane16_swap_b32_e32 v117, v120
	s_nop 1
	v_add_f32_e32 v120, v120, v117
	v_mov_b32_e32 v117, v120
	s_nop 1
	v_permlane32_swap_b32_e32 v117, v120
	s_nop 1
	v_add_f32_e32 v120, v120, v117
	v_add_f32_e32 v120, v120, v225
	v_rsq_f32_e32 v120, v120
	s_nop 0
	v_mul_f32_e32 v117, 0x3db504f3, v120
	v_cndmask_b32_e32 v120, v117, v120, vcc
	s_lshl_b32 vcc_hi, s48, 3
	v_readlane_b32 s7, v120, 0
	s_nop 1
	v_mov_b32_e32 v96, s7
	v_readlane_b32 s8, v120, 8
	v_mul_f32_e32 v30, v30, v96
	v_mul_f32_e32 v31, v31, v96
	v_readlane_b32 s9, v120, 4
	v_or_b32_e32 v101, 64, v93
	ds_write2st64_b32 v95, v30, v31 offset1:1
	v_cvt_pk_bf16_f32 v30, v30, s0
	v_readlane_b32 s10, v120, 12
	v_readlane_b32 s11, v120, 2
	v_readlane_b32 s40, v120, 6
	v_readlane_b32 s29, v120, 10
	v_readlane_b32 s41, v120, 14
	v_readlane_b32 s52, v120, 1
	v_readlane_b32 s53, v120, 9
	v_readlane_b32 s84, v120, 5
	v_readlane_b32 s85, v120, 13
	v_readlane_b32 vcc_lo, v120, 3
	v_readlane_b32 s28, v120, 11
	v_readlane_b32 s6, v120, 7
	v_readlane_b32 s7, v120, 15
	v_mov_b32_e32 v102, s8
	s_mul_i32 s8, s48, 0x440
	v_or_b32_e32 v218, s8, v93
	v_lshlrev_b32_e32 v218, 1, v218
	v_add_u32_e32 v218, s49, v218
	ds_write_b16 v218, v30
	v_cvt_pk_bf16_f32 v30, v31, s0
	ds_write_b16 v218, v30 offset:128
	v_mov_b32_e32 v30, s9
	v_mov_b32_e32 v103, s10
	v_mul_f32_e32 v104, v28, v30
	v_mul_f32_e32 v30, v29, v30
	v_mov_b32_e32 v28, v26
	v_mov_b32_e32 v29, v32
	v_pk_mul_f32 v[28:29], v[28:29], v[102:103]
	v_cvt_pk_bf16_f32 v26, v28, s0
	v_mov_b32_e32 v32, v27
	ds_write_b16 v218, v26 offset:17408
	v_pk_mul_f32 v[26:27], v[32:33], v[102:103]
	s_or_b32 s8, vcc_hi, 1
	v_cvt_pk_bf16_f32 v32, v26, s0
	ds_write_b16 v218, v32 offset:17536
	v_lshl_or_b32 v31, s8, 9, v94
	s_mulk_i32 s8, 0x88
	v_add_u32_e32 v31, 0, v31
	ds_write2st64_b32 v95, v28, v26 offset0:128 offset1:129
	ds_write2st64_b32 v31, v104, v30 offset1:1
	ds_write2st64_b32 v31, v29, v27 offset0:128 offset1:129
	v_cvt_pk_bf16_f32 v31, v104, s0
	ds_write_b16 v218, v31 offset:272
	v_cvt_pk_bf16_f32 v30, v30, s0
	ds_write_b16 v218, v30 offset:400
	v_cvt_pk_bf16_f32 v30, v29, s0
	ds_write_b16 v218, v30 offset:17680
	v_mov_b32_e32 v30, s11
	v_cvt_pk_bf16_f32 v32, v27, s0
	ds_write_b16 v218, v32 offset:17808
	v_mov_b32_e32 v31, v30
	v_mul_f32_e32 v24, v24, v31
	v_mul_f32_e32 v25, v25, v31
	v_lshl_or_b32 v31, s48, 12, v94
	s_add_i32 s9, s8, 0x88
	v_add_u32_e32 v32, 0, v31
	ds_write2st64_b32 v32, v24, v25 offset0:4 offset1:5
	v_cvt_pk_bf16_f32 v24, v24, s0
	ds_write_b16 v218, v24 offset:544
	v_cvt_pk_bf16_f32 v24, v25, s0
	v_mov_b32_e32 v94, s40
	v_mov_b32_e32 v30, s29
	ds_write_b16 v218, v24 offset:672
	v_mov_b32_e32 v31, s41
	v_mov_b32_e32 v33, v94
	v_mul_f32_e32 v94, v22, v33
	v_mul_f32_e32 v33, v23, v33
	v_mov_b32_e32 v22, v20
	v_mov_b32_e32 v23, v18
	v_pk_mul_f32 v[22:23], v[22:23], v[30:31]
	s_add_i32 s9, s8, 0x110
	v_cvt_pk_bf16_f32 v18, v22, s0
	ds_write_b16 v218, v18 offset:17952
	v_mov_b32_e32 v18, v21
	v_pk_mul_f32 v[18:19], v[18:19], v[30:31]
	v_cvt_pk_bf16_f32 v20, v18, s0
	ds_write2st64_b32 v32, v22, v18 offset0:132 offset1:133
	ds_write_b16 v218, v20 offset:18080
	ds_write2st64_b32 v32, v94, v33 offset0:6 offset1:7
	ds_write2st64_b32 v32, v23, v19 offset0:134 offset1:135
	v_cvt_pk_bf16_f32 v20, v94, s0
	ds_write_b16 v218, v20 offset:816
	v_cvt_pk_bf16_f32 v20, v33, s0
	ds_write_b16 v218, v20 offset:944
	v_cvt_pk_bf16_f32 v20, v23, s0
	ds_write_b16 v218, v20 offset:18224
	v_mov_b32_e32 v20, s52
	v_cvt_pk_bf16_f32 v21, v19, s0
	ds_write_b16 v218, v21 offset:18352
	v_mov_b32_e32 v21, v20
	s_add_i32 s9, s8, 0x198
	v_mul_f32_e32 v14, v14, v21
	v_mul_f32_e32 v15, v15, v21
	ds_write2st64_b32 v32, v14, v15 offset0:8 offset1:9
	v_cvt_pk_bf16_f32 v14, v14, s0
	ds_write_b16 v218, v14 offset:1088
	v_cvt_pk_bf16_f32 v14, v15, s0
	v_mov_b32_e32 v25, s84
	v_mov_b32_e32 v20, s53
	ds_write_b16 v218, v14 offset:1216
	v_mov_b32_e32 v21, s85
	v_mov_b32_e32 v24, v25
	v_mul_f32_e32 v25, v12, v24
	v_mul_f32_e32 v24, v13, v24
	v_mov_b32_e32 v12, v10
	v_mov_b32_e32 v13, v16
	v_pk_mul_f32 v[12:13], v[12:13], v[20:21]
	v_mov_b32_e32 v16, v11
	v_cvt_pk_bf16_f32 v10, v12, s0
	ds_write_b16 v218, v10 offset:18496
	v_pk_mul_f32 v[10:11], v[16:17], v[20:21]
	v_cvt_pk_bf16_f32 v14, v10, s0
	s_add_i32 s9, s8, 0x220
	ds_write2st64_b32 v32, v12, v10 offset0:136 offset1:137
	ds_write_b16 v218, v14 offset:18624
	ds_write2st64_b32 v32, v25, v24 offset0:10 offset1:11
	ds_write2st64_b32 v32, v13, v11 offset0:138 offset1:139
	v_cvt_pk_bf16_f32 v14, v25, s0
	ds_write_b16 v218, v14 offset:1360
	v_cvt_pk_bf16_f32 v14, v24, s0
	ds_write_b16 v218, v14 offset:1488
	v_cvt_pk_bf16_f32 v14, v13, s0
	ds_write_b16 v218, v14 offset:18768
	v_mov_b32_e32 v14, vcc_lo
	v_cvt_pk_bf16_f32 v15, v11, s0
	ds_write_b16 v218, v15 offset:18896
	v_mov_b32_e32 v15, v14
	s_add_i32 s9, s8, 0x2a8
	v_mul_f32_e32 v8, v8, v15
	v_mul_f32_e32 v9, v9, v15
	ds_write2st64_b32 v32, v8, v9 offset0:12 offset1:13
	v_cvt_pk_bf16_f32 v8, v8, s0
	ds_write_b16 v218, v8 offset:1632
	v_cvt_pk_bf16_f32 v8, v9, s0
	v_mov_b32_e32 v17, s6
	v_mov_b32_e32 v14, s28
	ds_write_b16 v218, v8 offset:1760
	v_mov_b32_e32 v15, s7
	v_mov_b32_e32 v9, v17
	v_mul_f32_e32 v17, v6, v9
	v_mul_f32_e32 v20, v7, v9
	v_mov_b32_e32 v6, v4
	v_mov_b32_e32 v7, v2
	v_pk_mul_f32 v[6:7], v[6:7], v[14:15]
	s_addk_i32 s8, 0x330
	v_cvt_pk_bf16_f32 v2, v6, s0
	ds_write_b16 v218, v2 offset:19040
	v_mov_b32_e32 v2, v5
	v_pk_mul_f32 v[8:9], v[2:3], v[14:15]
	v_cvt_pk_bf16_f32 v2, v8, s0
	ds_write2st64_b32 v32, v6, v8 offset0:140 offset1:141
	ds_write_b16 v218, v2 offset:19168
	ds_write2st64_b32 v32, v17, v20 offset0:14 offset1:15
	ds_write2st64_b32 v32, v7, v9 offset0:142 offset1:143
	v_cvt_pk_bf16_f32 v2, v17, s0
	ds_write_b16 v218, v2 offset:1904
	v_cvt_pk_bf16_f32 v2, v20, s0
	ds_write_b16 v218, v2 offset:2032
	v_cvt_pk_bf16_f32 v5, v6, v7
	v_bitop3_b32 v6, s48, v1, 7 bitop3:0x78
	v_cvt_pk_bf16_f32 v2, v7, s0
	v_lshlrev_b32_e32 v7, 7, v93
	s_add_i32 s6, 0, 0x14000
	v_lshlrev_b32_e32 v6, 4, v6
	s_ashr_i32 s53, s48, 1
	v_add3_u32 v6, s6, v7, v6
	s_and_b32 s6, s53, 1
	s_and_b32 s52, s48, 1
	s_cmp_eq_u32 s6, 0
	ds_write_b16 v218, v2 offset:19312
	v_cvt_pk_bf16_f32 v2, v9, s0
	s_cselect_b64 s[8:9], -1, 0
	s_bitcmp1_b32 s48, 0
	ds_write_b16 v218, v2 offset:19440
	v_cvt_pk_bf16_f32 v4, v12, v13
	v_cvt_pk_bf16_f32 v3, v22, v23
	v_cvt_pk_bf16_f32 v2, v28, v29
	s_cselect_b64 s[10:11], -1, 0
	ds_write_b128 v6, v[2:5]
	v_cvt_pk_bf16_f32 v5, v8, v9
	v_cvt_pk_bf16_f32 v4, v10, v11
	v_cvt_pk_bf16_f32 v3, v18, v19
	v_cvt_pk_bf16_f32 v2, v26, v27
	s_and_b64 s[8:9], s[8:9], s[10:11]
	ds_write_b128 v6, v[2:5] offset:8192
	v_and_b32_e32 v94, 31, v1
	v_lshrrev_b32_e32 v95, 5, v93
	v_mov_b32_e32 v2, 0
	s_and_b64 vcc, exec, s[8:9]
	v_mov_b32_e32 v3, 0
	v_mov_b32_e32 v4, 0
	v_mov_b32_e32 v5, 0
	v_mov_b32_e32 v6, 0
	v_mov_b32_e32 v7, 0
	v_mov_b32_e32 v8, 0
	v_mov_b32_e32 v9, 0
	v_mov_b32_e32 v10, 0
	v_mov_b32_e32 v11, 0
	v_mov_b32_e32 v12, 0
	v_mov_b32_e32 v13, 0
	v_mov_b32_e32 v14, 0
	v_mov_b32_e32 v15, 0
	v_mov_b32_e32 v16, 0
	v_mov_b32_e32 v17, 0
	s_waitcnt lgkmcnt(0)
	s_barrier
	s_cbranch_vccz .LBB0_136
	s_cmp_gt_u32 s48, 3
	v_lshlrev_b32_e32 v25, 2, v95
	s_mov_b64 s[28:29], -1
	s_cbranch_scc1 .LBB0_137
